# v16 + ticket window: first unit static (w_out1 tiles by bid, hides barrier latency for late arrivers), w_gate1 tiles stay dynamic
# speedup vs baseline: 1.0005x; 1.0005x over previous
; __global__ void __launch_bounds__(NTHREADS, 2) mk_fwd(Params P) {
;     ...
;     if (IN(7)) {
;         transpose_convert(lds, P.w_out + (size_t)2048 * 2048, WOUT1, 2048, 2048, G, bid);
;         transpose_convert(lds, P.w_gate + (size_t)2048 * 2048, WG1, 2048, 2048, G, bid);
;     }
;     if (IN(7)) attn_phase(lds, Qb, Kb, VTb, Zb, KPART, Y1, G, bid);
.Lgg6_f:
	global_atomic_add v251, v250, v252, s[54:55] offset:40 sc0
	v_mov_b32_e32 v47, s2
	v_add_u32_e32 v47, 0xffffff00, v47
	s_waitcnt vmcnt(0)
	v_readfirstlane_b32 s99, v251
	s_cmp_eq_u32 s99, 31
	s_cbranch_scc0 .Lgg6_n
	buffer_wbl2 sc1
	s_waitcnt vmcnt(0)
	v_mov_b32_e32 v253, 0x82c0
	global_atomic_add v253, v252, s[54:55]

; template <bool REMAP = false>
; __device__ __forceinline__ void transpose_convert(LAS unsigned char* lds, const float* src, bf16_t* dst, int K, int N, int G, int bid) {
;     ...
;     for (int t = bid; t < ntiles; t += G) {
;         const int k0 = (t / ntn) * 128, n0 = (t % ntn) * 64;
;         asm volatile("s_waitcnt lgkmcnt(0)" ::: "memory"); __builtin_amdgcn_s_barrier(); asm volatile("" ::: "memory");
; #pragma unroll
;         for (int i = 0; i < 4; ++i) {
; #pragma unroll
;             for (int j = 0; j < 4; ++j) tile[(r0 + 32 * i) * 65 + c4 * 4 + j] = v[i][j]; }
;         asm volatile("s_waitcnt lgkmcnt(0)" ::: "memory"); __builtin_amdgcn_s_barrier(); asm volatile("" ::: "memory");
;         if (t + G < ntiles) { const int k1 = ((t + G) / ntn) * 128, n1 = ((t + G) % ntn) * 64;
; #pragma unroll
;             for (int i = 0; i < 4; ++i) v[i] = __builtin_nontemporal_load((const f32x4*)(src + (size_t)(k1 + r0 + 32 * i) * N + n1 + c4 * 4)); }
.Ldyn7_top:
	s_waitcnt lgkmcnt(0)
	s_barrier
	s_add_u32 s10, s54, 0xa000
	s_addc_u32 s11, s55, 0
	s_and_saveexec_b64 s[18:19], s[12:13]
	s_cbranch_execz .Ldyn7_nofetch
	s_waitcnt vmcnt(4)
	v_add_u32_e32 v47, 0x100, v47
	ds_write_b32 v46, v47
	v_mov_b32_e32 v0, 0
	v_mov_b32_e32 v1, 1
	s_waitcnt lgkmcnt(0)
	global_atomic_add v47, v0, v1, s[10:11] sc0
